# indexer scoring: head-weight sum done with one packed multiply and one packed fma per 16-key tile
# speedup vs baseline: 1.0051x; 1.0051x over previous
.Lsc_bar:
	s_barrier
	s_and_b32 s53, s64, 3
	s_lshl_b32 s53, s53, 15
	v_add_u32_e32 v166, s53, v124
	v_add_u32_e32 v167, s53, v125
	ds_read_b128 v[26:29], v166
	ds_read_b128 v[30:33], v166 offset:2048
	ds_read_b128 v[34:37], v166 offset:4096
	ds_read_b128 v[38:41], v166 offset:6144
	ds_read_b128 v[42:45], v167
	ds_read_b128 v[46:49], v167 offset:2048
	ds_read_b128 v[50:53], v167 offset:4096
	ds_read_b128 v[54:57], v167 offset:6144
	ds_read_b128 v[58:61], v166 offset:8192
	ds_read_b128 v[62:65], v166 offset:10240
	ds_read_b128 v[66:69], v166 offset:12288
	ds_read_b128 v[70:73], v166 offset:14336
	ds_read_b128 v[74:77], v167 offset:8192
	ds_read_b128 v[78:81], v167 offset:10240
	ds_read_b128 v[82:85], v167 offset:12288
	ds_read_b128 v[86:89], v167 offset:14336
	s_cmp_eq_u32 s64, 0
	s_cbranch_scc1 .Lsc_first
	s_mov_b32 s5, s52
	s_add_i32 s67, s52, 1
	s_sub_i32 s52, s52, 64
	v_max_f32_e32 v106, 0, v106
	v_max_f32_e32 v107, 0, v107
	v_max_f32_e32 v108, 0, v108
	v_max_f32_e32 v109, 0, v109
	v_pk_mul_f32 v[160:161], v[2:3], v[106:107]
	v_pk_fma_f32 v[160:161], v[4:5], v[108:109], v[160:161]
	v_add_f32_e32 v156, v160, v161
	v_max_f32_e32 v110, 0, v110
	v_max_f32_e32 v111, 0, v111
	v_max_f32_e32 v112, 0, v112
	v_max_f32_e32 v113, 0, v113
	v_pk_mul_f32 v[160:161], v[2:3], v[110:111]
	v_pk_fma_f32 v[160:161], v[4:5], v[112:113], v[160:161]
	v_add_f32_e32 v157, v160, v161
	v_max_f32_e32 v114, 0, v114
	v_max_f32_e32 v115, 0, v115
	v_max_f32_e32 v116, 0, v116
	v_max_f32_e32 v117, 0, v117
	v_pk_mul_f32 v[160:161], v[2:3], v[114:115]
	v_pk_fma_f32 v[160:161], v[4:5], v[116:117], v[160:161]
	v_add_f32_e32 v158, v160, v161
	v_max_f32_e32 v118, 0, v118
	v_max_f32_e32 v119, 0, v119
	v_max_f32_e32 v120, 0, v120
	v_max_f32_e32 v121, 0, v121
	v_pk_mul_f32 v[160:161], v[2:3], v[118:119]
	s_waitcnt lgkmcnt(8)
	v_mfma_f32_16x16x32_bf16 v[90:93], v[10:13], v[26:29], 0
	v_pk_fma_f32 v[160:161], v[4:5], v[120:121], v[160:161]
	v_mfma_f32_16x16x32_bf16 v[94:97], v[10:13], v[30:33], 0
	v_add_f32_e32 v159, v160, v161
	v_mfma_f32_16x16x32_bf16 v[98:101], v[10:13], v[34:37], 0
	s_nop 1
	v_mfma_f32_16x16x32_bf16 v[102:105], v[10:13], v[38:41], 0
	v_permlane16_swap_b32_e32 v156, v157
	v_mfma_f32_16x16x32_bf16 v[90:93], v[6:9], v[42:45], v[90:93]
	v_permlane16_swap_b32_e32 v158, v159
	v_mfma_f32_16x16x32_bf16 v[94:97], v[6:9], v[46:49], v[94:97]
	v_add_f32_e32 v156, v156, v157
	v_mfma_f32_16x16x32_bf16 v[98:101], v[6:9], v[50:53], v[98:101]
	v_add_f32_e32 v158, v158, v159
	v_mfma_f32_16x16x32_bf16 v[102:105], v[6:9], v[54:57], v[102:105]
	s_nop 1
	v_permlane32_swap_b32_e32 v156, v158
	v_ashrrev_i32_e32 v164, 31, v156
	v_ashrrev_i32_e32 v165, 31, v158
	v_bitop3_b32 v164, v156, v164, v176 bitop3:0x1e
	v_bitop3_b32 v165, v158, v165, v176 bitop3:0x1e
	s_cmp_gt_i32 s5, 62
	s_cbranch_scc0 .Lsc_bndp
	v_and_b32_e32 v175, 0xffffff00, v164
	v_and_b32_e32 v165, 0xffffff00, v165
	s_branch .Lsc_stp

.Lsc_step1:
	ds_read_b128 v[26:29], v166 offset:16384
	ds_read_b128 v[30:33], v166 offset:18432
	ds_read_b128 v[34:37], v166 offset:20480
	ds_read_b128 v[38:41], v166 offset:22528
	ds_read_b128 v[42:45], v167 offset:16384
	ds_read_b128 v[46:49], v167 offset:18432
	ds_read_b128 v[50:53], v167 offset:20480
	ds_read_b128 v[54:57], v167 offset:22528
	s_waitcnt lgkmcnt(8)
	v_mfma_f32_16x16x32_bf16 v[106:109], v[10:13], v[58:61], 0
	s_mov_b32 s5, s52
	s_add_i32 s67, s52, 1
	s_sub_i32 s52, s52, 64
	v_max_f32_e32 v90, 0, v90
	v_max_f32_e32 v91, 0, v91
	v_mfma_f32_16x16x32_bf16 v[110:113], v[10:13], v[62:65], 0
	v_max_f32_e32 v92, 0, v92
	v_max_f32_e32 v93, 0, v93
	v_pk_mul_f32 v[160:161], v[2:3], v[90:91]
	v_pk_fma_f32 v[160:161], v[4:5], v[92:93], v[160:161]
	v_add_f32_e32 v156, v160, v161
	v_mfma_f32_16x16x32_bf16 v[114:117], v[10:13], v[66:69], 0
	v_max_f32_e32 v94, 0, v94
	v_max_f32_e32 v95, 0, v95
	v_max_f32_e32 v96, 0, v96
	v_max_f32_e32 v97, 0, v97
	v_pk_mul_f32 v[160:161], v[2:3], v[94:95]
	v_mfma_f32_16x16x32_bf16 v[118:121], v[10:13], v[70:73], 0
	v_pk_fma_f32 v[160:161], v[4:5], v[96:97], v[160:161]
	v_add_f32_e32 v157, v160, v161
	v_max_f32_e32 v98, 0, v98
	v_max_f32_e32 v99, 0, v99
	v_max_f32_e32 v100, 0, v100
	v_mfma_f32_16x16x32_bf16 v[106:109], v[6:9], v[74:77], v[106:109]
	v_max_f32_e32 v101, 0, v101
	v_pk_mul_f32 v[160:161], v[2:3], v[98:99]
	v_pk_fma_f32 v[160:161], v[4:5], v[100:101], v[160:161]
	v_add_f32_e32 v158, v160, v161
	v_max_f32_e32 v102, 0, v102
	v_mfma_f32_16x16x32_bf16 v[110:113], v[6:9], v[78:81], v[110:113]
	v_max_f32_e32 v103, 0, v103
	v_max_f32_e32 v104, 0, v104
	v_max_f32_e32 v105, 0, v105
	v_pk_mul_f32 v[160:161], v[2:3], v[102:103]
	v_pk_fma_f32 v[160:161], v[4:5], v[104:105], v[160:161]
	v_mfma_f32_16x16x32_bf16 v[114:117], v[6:9], v[82:85], v[114:117]
	v_add_f32_e32 v159, v160, v161
	s_nop 1
	v_permlane16_swap_b32_e32 v156, v157
	v_permlane16_swap_b32_e32 v158, v159
	v_add_f32_e32 v156, v156, v157
	v_mfma_f32_16x16x32_bf16 v[118:121], v[6:9], v[86:89], v[118:121]
	v_add_f32_e32 v158, v158, v159
	s_nop 1
	v_permlane32_swap_b32_e32 v156, v158
	v_ashrrev_i32_e32 v164, 31, v156
	v_ashrrev_i32_e32 v165, 31, v158
	v_bitop3_b32 v164, v156, v164, v176 bitop3:0x1e
	v_bitop3_b32 v165, v158, v165, v176 bitop3:0x1e
	s_cmp_gt_i32 s5, 62
	s_cbranch_scc0 .Lsc_bnda
	v_and_b32_e32 v172, 0xffffff00, v164
	v_and_b32_e32 v165, 0xffffff00, v165
	s_branch .Lsc_sta

.Lsc_sta:
	global_store_dword v168, v165, s[62:63]
	ds_read_b128 v[58:61], v166 offset:24576
	ds_read_b128 v[62:65], v166 offset:26624
	ds_read_b128 v[66:69], v166 offset:28672
	ds_read_b128 v[70:73], v166 offset:30720
	ds_read_b128 v[74:77], v167 offset:24576
	ds_read_b128 v[78:81], v167 offset:26624
	ds_read_b128 v[82:85], v167 offset:28672
	ds_read_b128 v[86:89], v167 offset:30720
	s_waitcnt lgkmcnt(8)
	v_mfma_f32_16x16x32_bf16 v[90:93], v[10:13], v[26:29], 0
	s_mov_b32 s5, s52
	s_add_i32 s67, s52, 1
	s_sub_i32 s52, s52, 64
	v_max_f32_e32 v106, 0, v106
	v_max_f32_e32 v107, 0, v107
	v_mfma_f32_16x16x32_bf16 v[94:97], v[10:13], v[30:33], 0
	v_max_f32_e32 v108, 0, v108
	v_max_f32_e32 v109, 0, v109
	v_pk_mul_f32 v[160:161], v[2:3], v[106:107]
	v_pk_fma_f32 v[160:161], v[4:5], v[108:109], v[160:161]
	v_add_f32_e32 v156, v160, v161
	v_mfma_f32_16x16x32_bf16 v[98:101], v[10:13], v[34:37], 0
	v_max_f32_e32 v110, 0, v110
	v_max_f32_e32 v111, 0, v111
	v_max_f32_e32 v112, 0, v112
	v_max_f32_e32 v113, 0, v113
	v_pk_mul_f32 v[160:161], v[2:3], v[110:111]
	v_mfma_f32_16x16x32_bf16 v[102:105], v[10:13], v[38:41], 0
	v_pk_fma_f32 v[160:161], v[4:5], v[112:113], v[160:161]
	v_add_f32_e32 v157, v160, v161
	v_max_f32_e32 v114, 0, v114
	v_max_f32_e32 v115, 0, v115
	v_max_f32_e32 v116, 0, v116
	v_mfma_f32_16x16x32_bf16 v[90:93], v[6:9], v[42:45], v[90:93]
	v_max_f32_e32 v117, 0, v117
	v_pk_mul_f32 v[160:161], v[2:3], v[114:115]
	v_pk_fma_f32 v[160:161], v[4:5], v[116:117], v[160:161]
	v_add_f32_e32 v158, v160, v161
	v_max_f32_e32 v118, 0, v118
	v_mfma_f32_16x16x32_bf16 v[94:97], v[6:9], v[46:49], v[94:97]
	v_max_f32_e32 v119, 0, v119
	v_max_f32_e32 v120, 0, v120
	v_max_f32_e32 v121, 0, v121
	v_pk_mul_f32 v[160:161], v[2:3], v[118:119]
	v_pk_fma_f32 v[160:161], v[4:5], v[120:121], v[160:161]
	v_mfma_f32_16x16x32_bf16 v[98:101], v[6:9], v[50:53], v[98:101]
	v_add_f32_e32 v159, v160, v161
	s_nop 1
	v_permlane16_swap_b32_e32 v156, v157
	v_permlane16_swap_b32_e32 v158, v159
	v_add_f32_e32 v156, v156, v157
	v_mfma_f32_16x16x32_bf16 v[102:105], v[6:9], v[54:57], v[102:105]
	v_add_f32_e32 v158, v158, v159
	s_nop 1
	v_permlane32_swap_b32_e32 v156, v158
	v_ashrrev_i32_e32 v164, 31, v156
	v_ashrrev_i32_e32 v165, 31, v158
	v_bitop3_b32 v164, v156, v164, v176 bitop3:0x1e
	v_bitop3_b32 v165, v158, v165, v176 bitop3:0x1e
	s_cmp_gt_i32 s5, 62
	s_cbranch_scc0 .Lsc_bndb
	v_and_b32_e32 v173, 0xffffff00, v164
	v_and_b32_e32 v165, 0xffffff00, v165
	s_branch .Lsc_stb

.Lsc_stb:
	global_store_dword v168, v165, s[62:63] offset:256
	s_waitcnt lgkmcnt(0)
	v_mfma_f32_16x16x32_bf16 v[106:109], v[10:13], v[58:61], 0
	s_mov_b32 s5, s52
	s_add_i32 s67, s52, 1
	s_sub_i32 s52, s52, 64
	v_max_f32_e32 v90, 0, v90
	v_max_f32_e32 v91, 0, v91
	v_mfma_f32_16x16x32_bf16 v[110:113], v[10:13], v[62:65], 0
	v_max_f32_e32 v92, 0, v92
	v_max_f32_e32 v93, 0, v93
	v_pk_mul_f32 v[160:161], v[2:3], v[90:91]
	v_pk_fma_f32 v[160:161], v[4:5], v[92:93], v[160:161]
	v_add_f32_e32 v156, v160, v161
	v_mfma_f32_16x16x32_bf16 v[114:117], v[10:13], v[66:69], 0
	v_max_f32_e32 v94, 0, v94
	v_max_f32_e32 v95, 0, v95
	v_max_f32_e32 v96, 0, v96
	v_max_f32_e32 v97, 0, v97
	v_pk_mul_f32 v[160:161], v[2:3], v[94:95]
	v_mfma_f32_16x16x32_bf16 v[118:121], v[10:13], v[70:73], 0
	v_pk_fma_f32 v[160:161], v[4:5], v[96:97], v[160:161]
	v_add_f32_e32 v157, v160, v161
	v_max_f32_e32 v98, 0, v98
	v_max_f32_e32 v99, 0, v99
	v_max_f32_e32 v100, 0, v100
	v_mfma_f32_16x16x32_bf16 v[106:109], v[6:9], v[74:77], v[106:109]
	v_max_f32_e32 v101, 0, v101
	v_pk_mul_f32 v[160:161], v[2:3], v[98:99]
	v_pk_fma_f32 v[160:161], v[4:5], v[100:101], v[160:161]
	v_add_f32_e32 v158, v160, v161
	v_max_f32_e32 v102, 0, v102
	v_mfma_f32_16x16x32_bf16 v[110:113], v[6:9], v[78:81], v[110:113]
	v_max_f32_e32 v103, 0, v103
	v_max_f32_e32 v104, 0, v104
	v_max_f32_e32 v105, 0, v105
	v_pk_mul_f32 v[160:161], v[2:3], v[102:103]
	v_pk_fma_f32 v[160:161], v[4:5], v[104:105], v[160:161]
	v_mfma_f32_16x16x32_bf16 v[114:117], v[6:9], v[82:85], v[114:117]
	v_add_f32_e32 v159, v160, v161
	s_nop 1
	v_permlane16_swap_b32_e32 v156, v157
	v_permlane16_swap_b32_e32 v158, v159
	v_add_f32_e32 v156, v156, v157
	v_mfma_f32_16x16x32_bf16 v[118:121], v[6:9], v[86:89], v[118:121]
	v_add_f32_e32 v158, v158, v159
	s_nop 1
	v_permlane32_swap_b32_e32 v156, v158
	v_ashrrev_i32_e32 v164, 31, v156
	v_ashrrev_i32_e32 v165, 31, v158
	v_bitop3_b32 v164, v156, v164, v176 bitop3:0x1e
	v_bitop3_b32 v165, v158, v165, v176 bitop3:0x1e
	s_cmp_gt_i32 s5, 62
	s_cbranch_scc0 .Lsc_bndc
	v_and_b32_e32 v174, 0xffffff00, v164
	v_and_b32_e32 v165, 0xffffff00, v165
	s_branch .Lsc_stc

.Lsc_stc:
	global_store_dword v168, v165, s[62:63] offset:512
	s_add_i32 s64, s64, 1
	s_add_u32 s62, s62, 0x400
	s_addc_u32 s63, s63, 0
	s_cmp_lt_u32 s64, s4
	s_cbranch_scc1 .Lsc_loop
	s_nop 7
	s_nop 7
	s_mov_b32 s5, s52
	s_add_i32 s67, s52, 1
	s_sub_i32 s52, s52, 64
	v_max_f32_e32 v106, 0, v106
	v_max_f32_e32 v107, 0, v107
	v_max_f32_e32 v108, 0, v108
	v_max_f32_e32 v109, 0, v109
	v_pk_mul_f32 v[160:161], v[2:3], v[106:107]
	v_pk_fma_f32 v[160:161], v[4:5], v[108:109], v[160:161]
	v_add_f32_e32 v156, v160, v161
	v_max_f32_e32 v110, 0, v110
	v_max_f32_e32 v111, 0, v111
	v_max_f32_e32 v112, 0, v112
	v_max_f32_e32 v113, 0, v113
	v_pk_mul_f32 v[160:161], v[2:3], v[110:111]
	v_pk_fma_f32 v[160:161], v[4:5], v[112:113], v[160:161]
	v_add_f32_e32 v157, v160, v161
	v_max_f32_e32 v114, 0, v114
	v_max_f32_e32 v115, 0, v115
	v_max_f32_e32 v116, 0, v116
	v_max_f32_e32 v117, 0, v117
	v_pk_mul_f32 v[160:161], v[2:3], v[114:115]
	v_pk_fma_f32 v[160:161], v[4:5], v[116:117], v[160:161]
	v_add_f32_e32 v158, v160, v161
	v_max_f32_e32 v118, 0, v118
	v_max_f32_e32 v119, 0, v119
	v_max_f32_e32 v120, 0, v120
	v_max_f32_e32 v121, 0, v121
	v_pk_mul_f32 v[160:161], v[2:3], v[118:119]
	v_pk_fma_f32 v[160:161], v[4:5], v[120:121], v[160:161]
	v_add_f32_e32 v159, v160, v161
	s_nop 1
	v_permlane16_swap_b32_e32 v156, v157
	v_permlane16_swap_b32_e32 v158, v159
	v_add_f32_e32 v156, v156, v157
	v_add_f32_e32 v158, v158, v159
	s_nop 1
	v_permlane32_swap_b32_e32 v156, v158
	v_ashrrev_i32_e32 v164, 31, v156
	v_ashrrev_i32_e32 v165, 31, v158
	v_bitop3_b32 v164, v156, v164, v176 bitop3:0x1e
	v_bitop3_b32 v165, v158, v165, v176 bitop3:0x1e
	s_cmp_gt_i32 s5, 62
	s_cbranch_scc0 .Lsc_bndd
	v_and_b32_e32 v175, 0xffffff00, v164
	v_and_b32_e32 v165, 0xffffff00, v165
	s_branch .Lsc_std
